# speedup vs baseline: 1.0028x; 1.0028x over previous
; __global__ void __launch_bounds__(NTH, 2) fwd_megakernel(Params P) {
;   extern __shared__ __attribute__((aligned(16))) char lds[];
;   cg::grid_group grid = cg::this_grid();
;   if (P.ws == nullptr) grid.sync();
_Z14fwd_megakernel6Params:
	v_readfirstlane_b32 s98, v0
	s_nop 3
	s_bfe_u32 s98, s98, 0x40006
	s_load_dwordx4 s[92:95], s[0:1], 0x60
	s_load_dwordx8 s[76:83], s[0:1], 0x40
	s_load_dwordx2 s[90:91], s[0:1], 0x70
	s_mov_b32 s88, s2
	s_add_u32 s2, s0, 0x70
	s_addc_u32 s3, s1, 0
	s_waitcnt lgkmcnt(0)
	s_cmp_eq_u64 s[94:95], 0
	s_mov_b64 s[4:5], 0
	s_cbranch_scc1 .LBB0_2
	v_and_b32_e32 v184, 0x3ff, v0
	s_load_dword s10, s[0:1], 0x78
	s_andn2_b64 vcc, exec, s[4:5]
	s_cbranch_vccz .LBB0_3
	s_branch .LBB0_14

; __device__ __forceinline__ u16 f2bf(float f) { return (u16)(cvtpk(f, f) & 0xffffu); }
; __device__ __forceinline__ float bf2f(u16 v) { return __uint_as_float(((unsigned)v) << 16); }
; __device__ __forceinline__ int crow(int r, int hi) { return (r & 3) + 8 * (r >> 2) + 4 * hi; }
; template <int MODE>
; __device__ __forceinline__ void attn_item(const Params& P, int b, int h, int qb, char* lds) {
;     ...
; #pragma unroll
;   for (int r = 0; r < 16; ++r) {
;     const float rl = __builtin_amdgcn_rcpf(ol[r]);
;     const size_t rowoff = (size_t)(b * SEQ + q0 + crow(r, hi)) * DM + h * 128;
; #pragma unroll
;     for (int d0 = 0; d0 < 4; ++d0) {
;       const size_t idx = rowoff + d0 * 32 + r32;
;       const float v = o[d0][r] * rl * bf2f(P_gate[idx]);
;       P_og[idx] = f2bf(v);
;     }
;   }
.LBB0_680:
	s_setprio 0
	s_add_i32 s56, s56, s49
	v_or_b32_e32 v4, s56, v170
	s_lshl_b32 s0, s33, 7
	s_ashr_i32 s1, s0, 31
	v_ashrrev_i32_e32 v5, 31, v4
	v_or_b32_e32 v2, s0, v169
	v_mov_b32_e32 v3, s1
	v_lshlrev_b64 v[6:7], 12, v[4:5]
	v_lshl_add_u64 v[6:7], v[6:7], 0, v[2:3]
	v_lshlrev_b64 v[6:7], 1, v[6:7]
	v_lshl_add_u64 v[8:9], s[14:15], 0, v[6:7]
	global_load_ushort v0, v[8:9], off
	v_or_b32_e32 v10, 64, v6
	v_mov_b32_e32 v11, v7
	v_lshl_add_u64 v[8:9], s[12:13], 0, v[6:7]
	v_lshl_add_u64 v[12:13], s[14:15], 0, v[10:11]
	v_or_b32_e32 v14, 0x80, v6
	v_mov_b32_e32 v15, v7
	v_or_b32_e32 v6, 0xc0, v6
	v_lshl_add_u64 v[96:97], s[14:15], 0, v[14:15]
	v_lshl_add_u64 v[98:99], s[14:15], 0, v[6:7]
	global_load_ushort v5, v[12:13], off
	global_load_ushort v110, v[96:97], off
	global_load_ushort v111, v[98:99], off
	v_rcp_f32_e32 v80, v80
	v_or_b32_e32 v12, 1, v4
	v_ashrrev_i32_e32 v13, 31, v12
	v_lshlrev_b64 v[12:13], 12, v[12:13]
	v_mul_f32_e32 v64, v64, v80
	v_lshl_add_u64 v[12:13], v[12:13], 0, v[2:3]
	v_mul_f32_e32 v48, v48, v80
	v_lshlrev_b64 v[12:13], 1, v[12:13]
	v_mul_f32_e32 v32, v32, v80
	v_mul_f32_e32 v16, v16, v80
	v_lshl_add_u64 v[10:11], s[12:13], 0, v[10:11]
	v_or_b32_e32 v100, 64, v12
	v_mov_b32_e32 v101, v13
	v_lshl_add_u64 v[14:15], s[12:13], 0, v[14:15]
	v_lshl_add_u64 v[6:7], s[12:13], 0, v[6:7]
	v_lshl_add_u64 v[96:97], s[14:15], 0, v[12:13]
	v_lshl_add_u64 v[98:99], s[12:13], 0, v[12:13]
	v_or_b32_e32 v102, 0x80, v12
	v_mov_b32_e32 v103, v13
	v_or_b32_e32 v12, 0xc0, v12
	v_lshl_add_u64 v[104:105], s[14:15], 0, v[100:101]
	v_lshl_add_u64 v[106:107], s[14:15], 0, v[102:103]
	v_lshl_add_u64 v[108:109], s[14:15], 0, v[12:13]
	v_lshl_add_u64 v[12:13], s[12:13], 0, v[12:13]
	s_add_i32 s55, s55, 1
	s_cmp_eq_u32 s55, 4
	s_waitcnt vmcnt(3)
	v_lshlrev_b32_e32 v0, 16, v0
	v_mul_f32_e32 v0, v64, v0
	v_cvt_pk_bf16_f32 v0, v0, v0
	global_store_short v[8:9], v0, off
	s_waitcnt vmcnt(3)
	v_lshlrev_b32_e32 v5, 16, v5
	s_waitcnt vmcnt(2)
	v_lshlrev_b32_e32 v64, 16, v110
	s_waitcnt vmcnt(1)
	v_lshlrev_b32_e32 v80, 16, v111
	v_mul_f32_e32 v5, v48, v5
	v_cvt_pk_bf16_f32 v0, v5, v5
	v_mul_f32_e32 v32, v32, v64
	v_mul_f32_e32 v16, v16, v80
	v_cvt_pk_bf16_f32 v5, v32, v32
	v_cvt_pk_bf16_f32 v8, v16, v16
	global_store_short v[10:11], v0, off
	global_store_short v[14:15], v5, off
	global_store_short v[6:7], v8, off
	global_load_ushort v0, v[96:97], off
	s_nop 0
	global_load_ushort v5, v[104:105], off
	s_nop 0
	global_load_ushort v104, v[106:107], off
	global_load_ushort v105, v[108:109], off
	v_rcp_f32_e32 v8, v81
	v_or_b32_e32 v6, 2, v4
	v_ashrrev_i32_e32 v7, 31, v6
	v_lshlrev_b64 v[6:7], 12, v[6:7]
	v_mul_f32_e32 v106, v65, v8
	v_mul_f32_e32 v107, v49, v8
	v_mul_f32_e32 v108, v33, v8
	v_mul_f32_e32 v109, v17, v8
	v_lshl_add_u64 v[6:7], v[6:7], 0, v[2:3]
	v_lshl_add_u64 v[32:33], s[12:13], 0, v[100:101]
	v_lshlrev_b64 v[6:7], 1, v[6:7]
	v_lshl_add_u64 v[8:9], s[14:15], 0, v[6:7]
	v_lshl_add_u64 v[10:11], s[12:13], 0, v[6:7]
	v_or_b32_e32 v14, 64, v6
	v_mov_b32_e32 v15, v7
	v_or_b32_e32 v16, 0x80, v6
	v_mov_b32_e32 v17, v7
	v_or_b32_e32 v6, 0xc0, v6
	v_lshl_add_u64 v[48:49], s[12:13], 0, v[102:103]
	v_lshl_add_u64 v[64:65], s[14:15], 0, v[14:15]
	v_lshl_add_u64 v[80:81], s[14:15], 0, v[16:17]
	v_lshl_add_u64 v[96:97], s[14:15], 0, v[6:7]
	v_lshl_add_u64 v[14:15], s[12:13], 0, v[14:15]
	v_lshl_add_u64 v[16:17], s[12:13], 0, v[16:17]
	v_lshl_add_u64 v[6:7], s[12:13], 0, v[6:7]
	s_waitcnt vmcnt(3)
	v_lshlrev_b32_e32 v0, 16, v0
	s_waitcnt vmcnt(2)
	v_lshlrev_b32_e32 v5, 16, v5
	s_waitcnt vmcnt(1)
	v_lshlrev_b32_e32 v100, 16, v104
	s_waitcnt vmcnt(0)
	v_lshlrev_b32_e32 v101, 16, v105
	v_mul_f32_e32 v0, v106, v0
	v_mul_f32_e32 v5, v107, v5
	v_mul_f32_e32 v100, v108, v100
	v_mul_f32_e32 v101, v109, v101
	v_cvt_pk_bf16_f32 v0, v0, v0
	v_cvt_pk_bf16_f32 v5, v5, v5
	v_cvt_pk_bf16_f32 v100, v100, v100
	v_cvt_pk_bf16_f32 v101, v101, v101
	global_store_short v[98:99], v0, off
	global_store_short v[32:33], v5, off
	global_store_short v[48:49], v100, off
	global_store_short v[12:13], v101, off
	global_load_ushort v0, v[8:9], off
	s_nop 0
	global_load_ushort v5, v[64:65], off
	global_load_ushort v100, v[80:81], off
	global_load_ushort v101, v[96:97], off
	v_rcp_f32_e32 v12, v82
	v_or_b32_e32 v8, 3, v4
	v_ashrrev_i32_e32 v9, 31, v8
	v_lshlrev_b64 v[8:9], 12, v[8:9]
	v_mul_f32_e32 v66, v66, v12
	v_lshl_add_u64 v[8:9], v[8:9], 0, v[2:3]
	v_mul_f32_e32 v50, v50, v12
	v_mul_f32_e32 v34, v34, v12
	v_mul_f32_e32 v18, v18, v12
	v_lshlrev_b64 v[8:9], 1, v[8:9]
	v_or_b32_e32 v48, 64, v8
	v_mov_b32_e32 v49, v9
	v_lshl_add_u64 v[12:13], s[14:15], 0, v[8:9]
	v_lshl_add_u64 v[32:33], s[12:13], 0, v[8:9]
	v_or_b32_e32 v64, 0x80, v8
	v_mov_b32_e32 v65, v9
	v_or_b32_e32 v8, 0xc0, v8
	v_lshl_add_u64 v[80:81], s[14:15], 0, v[48:49]
	v_lshl_add_u64 v[96:97], s[14:15], 0, v[64:65]
	v_lshl_add_u64 v[98:99], s[14:15], 0, v[8:9]
	v_lshl_add_u64 v[8:9], s[12:13], 0, v[8:9]
	s_waitcnt vmcnt(3)
	v_lshlrev_b32_e32 v0, 16, v0
	s_waitcnt vmcnt(2)
	v_lshlrev_b32_e32 v5, 16, v5
	s_waitcnt vmcnt(1)
	v_lshlrev_b32_e32 v82, 16, v100
	s_waitcnt vmcnt(0)
; __device__ __forceinline__ u16 f2bf(float f) { return (u16)(cvtpk(f, f) & 0xffffu); }
; __device__ __forceinline__ float bf2f(u16 v) { return __uint_as_float(((unsigned)v) << 16); }
; __device__ __forceinline__ int crow(int r, int hi) { return (r & 3) + 8 * (r >> 2) + 4 * hi; }
; template <int MODE>
; __device__ __forceinline__ void attn_item(const Params& P, int b, int h, int qb, char* lds) {
;     ...
; #pragma unroll
;   for (int r = 0; r < 16; ++r) {
;     const float rl = __builtin_amdgcn_rcpf(ol[r]);
;     const size_t rowoff = (size_t)(b * SEQ + q0 + crow(r, hi)) * DM + h * 128;
; #pragma unroll
;     for (int d0 = 0; d0 < 4; ++d0) {
;       const size_t idx = rowoff + d0 * 32 + r32;
;       const float v = o[d0][r] * rl * bf2f(P_gate[idx]);
;       P_og[idx] = f2bf(v);
;     }
;   }
	v_lshlrev_b32_e32 v100, 16, v101
	v_mul_f32_e32 v0, v66, v0
	v_mul_f32_e32 v5, v50, v5
	v_mul_f32_e32 v34, v34, v82
	v_mul_f32_e32 v18, v18, v100
	v_cvt_pk_bf16_f32 v0, v0, v0
	v_cvt_pk_bf16_f32 v5, v5, v5
	v_cvt_pk_bf16_f32 v34, v34, v34
	v_cvt_pk_bf16_f32 v18, v18, v18
	global_store_short v[10:11], v0, off
	global_store_short v[14:15], v5, off
	global_store_short v[16:17], v34, off
	global_store_short v[6:7], v18, off
	global_load_ushort v0, v[12:13], off
	s_nop 0
	global_load_ushort v5, v[80:81], off
	global_load_ushort v66, v[96:97], off
	s_nop 0
	global_load_ushort v80, v[98:99], off
	v_rcp_f32_e32 v10, v83
	v_or_b32_e32 v6, 8, v4
	v_ashrrev_i32_e32 v7, 31, v6
	v_lshlrev_b64 v[6:7], 12, v[6:7]
	v_mul_f32_e32 v67, v67, v10
	v_mul_f32_e32 v81, v51, v10
	v_mul_f32_e32 v82, v35, v10
	v_mul_f32_e32 v83, v19, v10
	v_lshl_add_u64 v[6:7], v[6:7], 0, v[2:3]
	v_lshlrev_b64 v[6:7], 1, v[6:7]
	v_lshl_add_u64 v[10:11], s[14:15], 0, v[6:7]
	v_lshl_add_u64 v[12:13], s[12:13], 0, v[6:7]
	v_or_b32_e32 v14, 64, v6
	v_mov_b32_e32 v15, v7
	v_or_b32_e32 v16, 0x80, v6
	v_mov_b32_e32 v17, v7
	v_or_b32_e32 v6, 0xc0, v6
	v_lshl_add_u64 v[18:19], s[12:13], 0, v[48:49]
	v_lshl_add_u64 v[34:35], s[12:13], 0, v[64:65]
	v_lshl_add_u64 v[48:49], s[14:15], 0, v[14:15]
	v_lshl_add_u64 v[50:51], s[14:15], 0, v[16:17]
	v_lshl_add_u64 v[64:65], s[14:15], 0, v[6:7]
	v_lshl_add_u64 v[14:15], s[12:13], 0, v[14:15]
	v_lshl_add_u64 v[16:17], s[12:13], 0, v[16:17]
	v_lshl_add_u64 v[6:7], s[12:13], 0, v[6:7]
	s_waitcnt vmcnt(3)
	v_lshlrev_b32_e32 v0, 16, v0
	s_waitcnt vmcnt(2)
	v_lshlrev_b32_e32 v5, 16, v5
	s_waitcnt vmcnt(1)
	v_lshlrev_b32_e32 v66, 16, v66
	s_waitcnt vmcnt(0)
	v_lshlrev_b32_e32 v80, 16, v80
	v_mul_f32_e32 v0, v67, v0
	v_mul_f32_e32 v5, v81, v5
	v_mul_f32_e32 v66, v82, v66
	v_mul_f32_e32 v67, v83, v80
	v_cvt_pk_bf16_f32 v0, v0, v0
	v_cvt_pk_bf16_f32 v5, v5, v5
	v_cvt_pk_bf16_f32 v66, v66, v66
	v_cvt_pk_bf16_f32 v67, v67, v67
	global_store_short v[32:33], v0, off
	global_store_short v[18:19], v5, off
	global_store_short v[34:35], v66, off
	global_store_short v[8:9], v67, off
	global_load_ushort v0, v[10:11], off
	s_nop 0
	global_load_ushort v5, v[48:49], off
	global_load_ushort v66, v[50:51], off
	global_load_ushort v67, v[64:65], off
	v_rcp_f32_e32 v10, v84
	v_or_b32_e32 v8, 9, v4
	v_ashrrev_i32_e32 v9, 31, v8
	v_lshlrev_b64 v[8:9], 12, v[8:9]
	v_mul_f32_e32 v68, v68, v10
	v_lshl_add_u64 v[8:9], v[8:9], 0, v[2:3]
	v_mul_f32_e32 v52, v52, v10
	v_mul_f32_e32 v36, v36, v10
	v_mul_f32_e32 v20, v20, v10
	v_lshlrev_b64 v[8:9], 1, v[8:9]
	v_or_b32_e32 v34, 0x80, v8
	v_mov_b32_e32 v35, v9
	v_lshl_add_u64 v[10:11], s[14:15], 0, v[8:9]
	v_lshl_add_u64 v[18:19], s[12:13], 0, v[8:9]
	v_or_b32_e32 v32, 64, v8
	v_mov_b32_e32 v33, v9
	v_or_b32_e32 v8, 0xc0, v8
	v_lshl_add_u64 v[50:51], s[14:15], 0, v[34:35]
	v_lshl_add_u64 v[48:49], s[14:15], 0, v[32:33]
	v_lshl_add_u64 v[64:65], s[14:15], 0, v[8:9]
	v_lshl_add_u64 v[8:9], s[12:13], 0, v[8:9]
	s_waitcnt vmcnt(3)
	v_lshlrev_b32_e32 v0, 16, v0
	s_waitcnt vmcnt(2)
	v_lshlrev_b32_e32 v5, 16, v5
	s_waitcnt vmcnt(1)
	v_lshlrev_b32_e32 v66, 16, v66
	s_waitcnt vmcnt(0)
	v_lshlrev_b32_e32 v67, 16, v67
	v_mul_f32_e32 v0, v68, v0
	v_mul_f32_e32 v5, v52, v5
	v_mul_f32_e32 v36, v36, v66
	v_mul_f32_e32 v20, v20, v67
	v_cvt_pk_bf16_f32 v0, v0, v0
	v_cvt_pk_bf16_f32 v5, v5, v5
	v_cvt_pk_bf16_f32 v36, v36, v36
	v_cvt_pk_bf16_f32 v20, v20, v20
	global_store_short v[12:13], v0, off
	global_store_short v[14:15], v5, off
	global_store_short v[16:17], v36, off
	global_store_short v[6:7], v20, off
	global_load_ushort v0, v[10:11], off
	s_nop 0
	global_load_ushort v5, v[48:49], off
	s_nop 0
	global_load_ushort v50, v[50:51], off
	s_nop 0
	global_load_ushort v51, v[64:65], off
	v_rcp_f32_e32 v10, v85
	v_or_b32_e32 v6, 10, v4
	v_ashrrev_i32_e32 v7, 31, v6
	v_lshlrev_b64 v[6:7], 12, v[6:7]
	v_mul_f32_e32 v52, v69, v10
	v_mul_f32_e32 v53, v53, v10
	v_mul_f32_e32 v64, v37, v10
	v_mul_f32_e32 v65, v21, v10
	v_lshl_add_u64 v[6:7], v[6:7], 0, v[2:3]
	v_lshlrev_b64 v[6:7], 1, v[6:7]
	v_lshl_add_u64 v[10:11], s[14:15], 0, v[6:7]
	v_lshl_add_u64 v[12:13], s[12:13], 0, v[6:7]
	v_or_b32_e32 v14, 64, v6
	v_mov_b32_e32 v15, v7
	v_or_b32_e32 v16, 0x80, v6
	v_mov_b32_e32 v17, v7
	v_or_b32_e32 v6, 0xc0, v6
	v_lshl_add_u64 v[20:21], s[12:13], 0, v[32:33]
	v_lshl_add_u64 v[32:33], s[12:13], 0, v[34:35]
	v_lshl_add_u64 v[34:35], s[14:15], 0, v[14:15]
	v_lshl_add_u64 v[36:37], s[14:15], 0, v[16:17]
	v_lshl_add_u64 v[48:49], s[14:15], 0, v[6:7]
	v_lshl_add_u64 v[14:15], s[12:13], 0, v[14:15]
	v_lshl_add_u64 v[16:17], s[12:13], 0, v[16:17]
	v_lshl_add_u64 v[6:7], s[12:13], 0, v[6:7]
	s_waitcnt vmcnt(3)
	v_lshlrev_b32_e32 v0, 16, v0
	s_waitcnt vmcnt(2)
	v_lshlrev_b32_e32 v5, 16, v5
	s_waitcnt vmcnt(1)
	v_lshlrev_b32_e32 v50, 16, v50
	s_waitcnt vmcnt(0)
	v_lshlrev_b32_e32 v51, 16, v51
	v_mul_f32_e32 v0, v52, v0
	v_mul_f32_e32 v5, v53, v5
	v_mul_f32_e32 v50, v64, v50
	v_mul_f32_e32 v51, v65, v51
	v_cvt_pk_bf16_f32 v0, v0, v0
	v_cvt_pk_bf16_f32 v5, v5, v5
	v_cvt_pk_bf16_f32 v50, v50, v50
	v_cvt_pk_bf16_f32 v51, v51, v51
	global_store_short v[18:19], v0, off
	global_store_short v[20:21], v5, off
	global_store_short v[32:33], v50, off
	global_store_short v[8:9], v51, off
	global_load_ushort v0, v[10:11], off
	s_nop 0
	global_load_ushort v5, v[34:35], off
	global_load_ushort v50, v[36:37], off
	global_load_ushort v51, v[48:49], off
	v_rcp_f32_e32 v10, v86
	v_or_b32_e32 v8, 11, v4
	v_ashrrev_i32_e32 v9, 31, v8
	v_lshlrev_b64 v[8:9], 12, v[8:9]
	v_mul_f32_e32 v52, v70, v10
	v_lshl_add_u64 v[8:9], v[8:9], 0, v[2:3]
	v_mul_f32_e32 v53, v54, v10
	v_mul_f32_e32 v38, v38, v10
	v_mul_f32_e32 v22, v22, v10
	v_lshlrev_b64 v[8:9], 1, v[8:9]
	v_lshl_add_u64 v[10:11], s[14:15], 0, v[8:9]
	v_lshl_add_u64 v[18:19], s[12:13], 0, v[8:9]
	v_or_b32_e32 v20, 64, v8
	v_or_b32_e32 v32, 0x80, v8
	v_or_b32_e32 v8, 0xc0, v8
	v_mov_b32_e32 v21, v9
	v_mov_b32_e32 v33, v9
	v_lshl_add_u64 v[48:49], s[14:15], 0, v[8:9]
	v_lshl_add_u64 v[34:35], s[14:15], 0, v[20:21]
	v_lshl_add_u64 v[36:37], s[14:15], 0, v[32:33]
	v_lshl_add_u64 v[20:21], s[12:13], 0, v[20:21]
	v_lshl_add_u64 v[8:9], s[12:13], 0, v[8:9]
	s_waitcnt vmcnt(3)
; __device__ __forceinline__ u16 f2bf(float f) { return (u16)(cvtpk(f, f) & 0xffffu); }
; __device__ __forceinline__ float bf2f(u16 v) { return __uint_as_float(((unsigned)v) << 16); }
; __device__ __forceinline__ int crow(int r, int hi) { return (r & 3) + 8 * (r >> 2) + 4 * hi; }
; template <int MODE>
; __device__ __forceinline__ void attn_item(const Params& P, int b, int h, int qb, char* lds) {
;     ...
; #pragma unroll
;   for (int r = 0; r < 16; ++r) {
;     const float rl = __builtin_amdgcn_rcpf(ol[r]);
;     const size_t rowoff = (size_t)(b * SEQ + q0 + crow(r, hi)) * DM + h * 128;
; #pragma unroll
;     for (int d0 = 0; d0 < 4; ++d0) {
;       const size_t idx = rowoff + d0 * 32 + r32;
;       const float v = o[d0][r] * rl * bf2f(P_gate[idx]);
;       P_og[idx] = f2bf(v);
;     }
;   }
	v_lshlrev_b32_e32 v0, 16, v0
	s_waitcnt vmcnt(2)
	v_lshlrev_b32_e32 v5, 16, v5
	s_waitcnt vmcnt(1)
	v_lshlrev_b32_e32 v50, 16, v50
	s_waitcnt vmcnt(0)
	v_lshlrev_b32_e32 v51, 16, v51
	v_mul_f32_e32 v0, v52, v0
	v_mul_f32_e32 v5, v53, v5
	v_mul_f32_e32 v38, v38, v50
	v_mul_f32_e32 v22, v22, v51
	v_cvt_pk_bf16_f32 v0, v0, v0
	v_cvt_pk_bf16_f32 v5, v5, v5
	v_cvt_pk_bf16_f32 v38, v38, v38
	v_cvt_pk_bf16_f32 v22, v22, v22
	global_store_short v[12:13], v0, off
	global_store_short v[14:15], v5, off
	global_store_short v[16:17], v38, off
	global_store_short v[6:7], v22, off
	global_load_ushort v0, v[10:11], off
	s_nop 0
	global_load_ushort v5, v[34:35], off
	global_load_ushort v38, v[36:37], off
	s_nop 0
	global_load_ushort v48, v[48:49], off
	v_rcp_f32_e32 v10, v87
	v_or_b32_e32 v6, 16, v4
	v_ashrrev_i32_e32 v7, 31, v6
	v_lshlrev_b64 v[6:7], 12, v[6:7]
	v_mul_f32_e32 v49, v71, v10
	v_mul_f32_e32 v50, v55, v10
	v_mul_f32_e32 v39, v39, v10
	v_mul_f32_e32 v51, v23, v10
	v_lshl_add_u64 v[6:7], v[6:7], 0, v[2:3]
	v_lshlrev_b64 v[6:7], 1, v[6:7]
	v_lshl_add_u64 v[10:11], s[14:15], 0, v[6:7]
	v_lshl_add_u64 v[12:13], s[12:13], 0, v[6:7]
	v_or_b32_e32 v14, 64, v6
	v_mov_b32_e32 v15, v7
	v_or_b32_e32 v16, 0x80, v6
	v_mov_b32_e32 v17, v7
	v_or_b32_e32 v6, 0xc0, v6
	v_lshl_add_u64 v[22:23], s[12:13], 0, v[32:33]
	v_lshl_add_u64 v[32:33], s[14:15], 0, v[14:15]
	v_lshl_add_u64 v[34:35], s[14:15], 0, v[16:17]
	v_lshl_add_u64 v[36:37], s[14:15], 0, v[6:7]
	v_lshl_add_u64 v[14:15], s[12:13], 0, v[14:15]
	v_lshl_add_u64 v[16:17], s[12:13], 0, v[16:17]
	v_lshl_add_u64 v[6:7], s[12:13], 0, v[6:7]
	s_waitcnt vmcnt(3)
	v_lshlrev_b32_e32 v0, 16, v0
	s_waitcnt vmcnt(2)
	v_lshlrev_b32_e32 v5, 16, v5
	s_waitcnt vmcnt(1)
	v_lshlrev_b32_e32 v38, 16, v38
	s_waitcnt vmcnt(0)
	v_lshlrev_b32_e32 v48, 16, v48
	v_mul_f32_e32 v0, v49, v0
	v_mul_f32_e32 v5, v50, v5
	v_mul_f32_e32 v38, v39, v38
	v_mul_f32_e32 v39, v51, v48
	v_cvt_pk_bf16_f32 v0, v0, v0
	v_cvt_pk_bf16_f32 v5, v5, v5
	v_cvt_pk_bf16_f32 v38, v38, v38
	v_cvt_pk_bf16_f32 v39, v39, v39
	global_store_short v[18:19], v0, off
	global_store_short v[20:21], v5, off
	global_store_short v[22:23], v38, off
	global_store_short v[8:9], v39, off
	global_load_ushort v0, v[10:11], off
	s_nop 0
	global_load_ushort v5, v[32:33], off
	global_load_ushort v38, v[34:35], off
	global_load_ushort v39, v[36:37], off
	v_rcp_f32_e32 v10, v88
	v_or_b32_e32 v8, 17, v4
	v_ashrrev_i32_e32 v9, 31, v8
	v_lshlrev_b64 v[8:9], 12, v[8:9]
	v_mul_f32_e32 v48, v72, v10
	v_lshl_add_u64 v[8:9], v[8:9], 0, v[2:3]
	v_mul_f32_e32 v49, v56, v10
	v_mul_f32_e32 v40, v40, v10
	v_mul_f32_e32 v24, v24, v10
	v_lshlrev_b64 v[8:9], 1, v[8:9]
	v_lshl_add_u64 v[10:11], s[14:15], 0, v[8:9]
	v_lshl_add_u64 v[18:19], s[12:13], 0, v[8:9]
	v_or_b32_e32 v20, 64, v8
	v_or_b32_e32 v22, 0x80, v8
	v_or_b32_e32 v8, 0xc0, v8
	v_mov_b32_e32 v21, v9
	v_mov_b32_e32 v23, v9
	v_lshl_add_u64 v[36:37], s[14:15], 0, v[8:9]
	v_lshl_add_u64 v[32:33], s[14:15], 0, v[20:21]
	v_lshl_add_u64 v[34:35], s[14:15], 0, v[22:23]
	v_lshl_add_u64 v[20:21], s[12:13], 0, v[20:21]
	v_lshl_add_u64 v[22:23], s[12:13], 0, v[22:23]
	v_lshl_add_u64 v[8:9], s[12:13], 0, v[8:9]
	s_waitcnt vmcnt(3)
	v_lshlrev_b32_e32 v0, 16, v0
	s_waitcnt vmcnt(2)
	v_lshlrev_b32_e32 v5, 16, v5
	s_waitcnt vmcnt(1)
	v_lshlrev_b32_e32 v38, 16, v38
	s_waitcnt vmcnt(0)
	v_lshlrev_b32_e32 v39, 16, v39
	v_mul_f32_e32 v0, v48, v0
	v_mul_f32_e32 v5, v49, v5
	v_mul_f32_e32 v38, v40, v38
	v_mul_f32_e32 v24, v24, v39
	v_cvt_pk_bf16_f32 v0, v0, v0
	v_cvt_pk_bf16_f32 v5, v5, v5
	v_cvt_pk_bf16_f32 v38, v38, v38
	v_cvt_pk_bf16_f32 v24, v24, v24
	global_store_short v[12:13], v0, off
	global_store_short v[14:15], v5, off
	global_store_short v[16:17], v38, off
	global_store_short v[6:7], v24, off
	global_load_ushort v0, v[10:11], off
	s_nop 0
	global_load_ushort v5, v[32:33], off
	global_load_ushort v38, v[34:35], off
	s_nop 0
	global_load_ushort v36, v[36:37], off
	v_rcp_f32_e32 v10, v89
	v_or_b32_e32 v6, 18, v4
	v_ashrrev_i32_e32 v7, 31, v6
	v_lshlrev_b64 v[6:7], 12, v[6:7]
	v_mul_f32_e32 v37, v73, v10
	v_mul_f32_e32 v39, v57, v10
	v_mul_f32_e32 v40, v41, v10
	v_mul_f32_e32 v41, v25, v10
	v_lshl_add_u64 v[6:7], v[6:7], 0, v[2:3]
	v_lshlrev_b64 v[6:7], 1, v[6:7]
	v_lshl_add_u64 v[10:11], s[14:15], 0, v[6:7]
	v_lshl_add_u64 v[12:13], s[12:13], 0, v[6:7]
	v_or_b32_e32 v14, 64, v6
	v_mov_b32_e32 v15, v7
	v_or_b32_e32 v16, 0x80, v6
	v_mov_b32_e32 v17, v7
	v_or_b32_e32 v6, 0xc0, v6
	v_lshl_add_u64 v[24:25], s[14:15], 0, v[14:15]
	v_lshl_add_u64 v[32:33], s[14:15], 0, v[16:17]
	v_lshl_add_u64 v[34:35], s[14:15], 0, v[6:7]
	v_lshl_add_u64 v[14:15], s[12:13], 0, v[14:15]
	v_lshl_add_u64 v[16:17], s[12:13], 0, v[16:17]
	v_lshl_add_u64 v[6:7], s[12:13], 0, v[6:7]
	s_waitcnt vmcnt(3)
	v_lshlrev_b32_e32 v0, 16, v0
	s_waitcnt vmcnt(2)
	v_lshlrev_b32_e32 v5, 16, v5
	s_waitcnt vmcnt(1)
	v_lshlrev_b32_e32 v38, 16, v38
	s_waitcnt vmcnt(0)
	v_lshlrev_b32_e32 v36, 16, v36
	v_mul_f32_e32 v0, v37, v0
	v_mul_f32_e32 v5, v39, v5
	v_mul_f32_e32 v37, v40, v38
	v_mul_f32_e32 v36, v41, v36
	v_cvt_pk_bf16_f32 v0, v0, v0
	v_cvt_pk_bf16_f32 v5, v5, v5
	v_cvt_pk_bf16_f32 v37, v37, v37
	v_cvt_pk_bf16_f32 v36, v36, v36
	global_store_short v[18:19], v0, off
	global_store_short v[20:21], v5, off
	global_store_short v[22:23], v37, off
	global_store_short v[8:9], v36, off
	global_load_ushort v0, v[10:11], off
	s_nop 0
	global_load_ushort v5, v[24:25], off
	global_load_ushort v36, v[32:33], off
	global_load_ushort v37, v[34:35], off
	v_rcp_f32_e32 v10, v90
	v_or_b32_e32 v8, 19, v4
	v_ashrrev_i32_e32 v9, 31, v8
	v_lshlrev_b64 v[8:9], 12, v[8:9]
	v_mul_f32_e32 v38, v74, v10
	v_lshl_add_u64 v[8:9], v[8:9], 0, v[2:3]
	v_mul_f32_e32 v39, v58, v10
	v_mul_f32_e32 v40, v42, v10
	v_mul_f32_e32 v26, v26, v10
	v_lshlrev_b64 v[8:9], 1, v[8:9]
	v_lshl_add_u64 v[10:11], s[14:15], 0, v[8:9]
	v_lshl_add_u64 v[18:19], s[12:13], 0, v[8:9]
	v_or_b32_e32 v20, 64, v8
	v_or_b32_e32 v22, 0x80, v8
	v_or_b32_e32 v8, 0xc0, v8
	v_mov_b32_e32 v21, v9
	v_mov_b32_e32 v23, v9
	v_lshl_add_u64 v[34:35], s[14:15], 0, v[8:9]
	v_lshl_add_u64 v[24:25], s[14:15], 0, v[20:21]
	v_lshl_add_u64 v[32:33], s[14:15], 0, v[22:23]
	v_lshl_add_u64 v[20:21], s[12:13], 0, v[20:21]
	v_lshl_add_u64 v[22:23], s[12:13], 0, v[22:23]
	v_lshl_add_u64 v[8:9], s[12:13], 0, v[8:9]
	s_waitcnt vmcnt(3)
; __device__ __forceinline__ u16 f2bf(float f) { return (u16)(cvtpk(f, f) & 0xffffu); }
; __device__ __forceinline__ float bf2f(u16 v) { return __uint_as_float(((unsigned)v) << 16); }
; __device__ __forceinline__ int crow(int r, int hi) { return (r & 3) + 8 * (r >> 2) + 4 * hi; }
; template <int MODE>
; __device__ __forceinline__ void attn_item(const Params& P, int b, int h, int qb, char* lds) {
;     ...
; #pragma unroll
;   for (int r = 0; r < 16; ++r) {
;     const float rl = __builtin_amdgcn_rcpf(ol[r]);
;     const size_t rowoff = (size_t)(b * SEQ + q0 + crow(r, hi)) * DM + h * 128;
; #pragma unroll
;     for (int d0 = 0; d0 < 4; ++d0) {
;       const size_t idx = rowoff + d0 * 32 + r32;
;       const float v = o[d0][r] * rl * bf2f(P_gate[idx]);
;       P_og[idx] = f2bf(v);
;     }
;   }
	v_lshlrev_b32_e32 v0, 16, v0
	s_waitcnt vmcnt(2)
	v_lshlrev_b32_e32 v5, 16, v5
	s_waitcnt vmcnt(1)
	v_lshlrev_b32_e32 v36, 16, v36
	s_waitcnt vmcnt(0)
	v_lshlrev_b32_e32 v37, 16, v37
	v_mul_f32_e32 v0, v38, v0
	v_mul_f32_e32 v5, v39, v5
	v_mul_f32_e32 v36, v40, v36
	v_mul_f32_e32 v26, v26, v37
	v_cvt_pk_bf16_f32 v0, v0, v0
	v_cvt_pk_bf16_f32 v5, v5, v5
	v_cvt_pk_bf16_f32 v36, v36, v36
	v_cvt_pk_bf16_f32 v26, v26, v26
	global_store_short v[12:13], v0, off
	global_store_short v[14:15], v5, off
	global_store_short v[16:17], v36, off
	global_store_short v[6:7], v26, off
	global_load_ushort v0, v[10:11], off
	s_nop 0
	global_load_ushort v5, v[24:25], off
	global_load_ushort v36, v[32:33], off
	s_nop 0
	global_load_ushort v34, v[34:35], off
	v_rcp_f32_e32 v10, v91
	v_or_b32_e32 v6, 24, v4
	v_ashrrev_i32_e32 v7, 31, v6
	v_lshlrev_b64 v[6:7], 12, v[6:7]
	v_mul_f32_e32 v35, v75, v10
	v_mul_f32_e32 v37, v59, v10
	v_mul_f32_e32 v38, v43, v10
	v_mul_f32_e32 v39, v27, v10
	v_lshl_add_u64 v[6:7], v[6:7], 0, v[2:3]
	v_lshlrev_b64 v[6:7], 1, v[6:7]
	v_lshl_add_u64 v[10:11], s[14:15], 0, v[6:7]
	v_lshl_add_u64 v[12:13], s[12:13], 0, v[6:7]
	v_or_b32_e32 v14, 64, v6
	v_mov_b32_e32 v15, v7
	v_or_b32_e32 v16, 0x80, v6
	v_mov_b32_e32 v17, v7
	v_or_b32_e32 v6, 0xc0, v6
	v_lshl_add_u64 v[24:25], s[14:15], 0, v[14:15]
	v_lshl_add_u64 v[26:27], s[14:15], 0, v[16:17]
	v_lshl_add_u64 v[32:33], s[14:15], 0, v[6:7]
	v_lshl_add_u64 v[14:15], s[12:13], 0, v[14:15]
	v_lshl_add_u64 v[16:17], s[12:13], 0, v[16:17]
	v_lshl_add_u64 v[6:7], s[12:13], 0, v[6:7]
	s_waitcnt vmcnt(3)
	v_lshlrev_b32_e32 v0, 16, v0
	s_waitcnt vmcnt(2)
	v_lshlrev_b32_e32 v5, 16, v5
	s_waitcnt vmcnt(1)
	v_lshlrev_b32_e32 v36, 16, v36
	s_waitcnt vmcnt(0)
	v_lshlrev_b32_e32 v34, 16, v34
	v_mul_f32_e32 v0, v35, v0
	v_mul_f32_e32 v5, v37, v5
	v_mul_f32_e32 v35, v38, v36
	v_mul_f32_e32 v34, v39, v34
	v_cvt_pk_bf16_f32 v0, v0, v0
	v_cvt_pk_bf16_f32 v5, v5, v5
	v_cvt_pk_bf16_f32 v35, v35, v35
	v_cvt_pk_bf16_f32 v34, v34, v34
	global_store_short v[18:19], v0, off
	global_store_short v[20:21], v5, off
	global_store_short v[22:23], v35, off
	global_store_short v[8:9], v34, off
	global_load_ushort v0, v[10:11], off
	s_nop 0
	global_load_ushort v5, v[24:25], off
	global_load_ushort v34, v[26:27], off
	global_load_ushort v35, v[32:33], off
	v_rcp_f32_e32 v10, v92
	v_or_b32_e32 v8, 25, v4
	v_ashrrev_i32_e32 v9, 31, v8
	v_lshlrev_b64 v[8:9], 12, v[8:9]
	v_mul_f32_e32 v36, v76, v10
	v_lshl_add_u64 v[8:9], v[8:9], 0, v[2:3]
	v_mul_f32_e32 v37, v60, v10
	v_mul_f32_e32 v38, v44, v10
	v_mul_f32_e32 v28, v28, v10
	v_lshlrev_b64 v[8:9], 1, v[8:9]
	v_lshl_add_u64 v[10:11], s[14:15], 0, v[8:9]
	v_lshl_add_u64 v[18:19], s[12:13], 0, v[8:9]
	v_or_b32_e32 v20, 64, v8
	v_or_b32_e32 v22, 0x80, v8
	v_or_b32_e32 v8, 0xc0, v8
	v_mov_b32_e32 v21, v9
	v_mov_b32_e32 v23, v9
	v_lshl_add_u64 v[32:33], s[14:15], 0, v[8:9]
	v_lshl_add_u64 v[24:25], s[14:15], 0, v[20:21]
	v_lshl_add_u64 v[26:27], s[14:15], 0, v[22:23]
	v_lshl_add_u64 v[20:21], s[12:13], 0, v[20:21]
	v_lshl_add_u64 v[22:23], s[12:13], 0, v[22:23]
	v_lshl_add_u64 v[8:9], s[12:13], 0, v[8:9]
	s_waitcnt vmcnt(3)
	v_lshlrev_b32_e32 v0, 16, v0
	s_waitcnt vmcnt(2)
	v_lshlrev_b32_e32 v5, 16, v5
	s_waitcnt vmcnt(1)
	v_lshlrev_b32_e32 v34, 16, v34
	s_waitcnt vmcnt(0)
; __device__ __forceinline__ u16 f2bf(float f) { return (u16)(cvtpk(f, f) & 0xffffu); }
; __device__ __forceinline__ float bf2f(u16 v) { return __uint_as_float(((unsigned)v) << 16); }
; __device__ __forceinline__ int crow(int r, int hi) { return (r & 3) + 8 * (r >> 2) + 4 * hi; }
; template <int MODE>
; __device__ __forceinline__ void attn_item(const Params& P, int b, int h, int qb, char* lds) {
;     ...
; #pragma unroll
;   for (int r = 0; r < 16; ++r) {
;     const float rl = __builtin_amdgcn_rcpf(ol[r]);
;     const size_t rowoff = (size_t)(b * SEQ + q0 + crow(r, hi)) * DM + h * 128;
; #pragma unroll
;     for (int d0 = 0; d0 < 4; ++d0) {
;       const size_t idx = rowoff + d0 * 32 + r32;
;       const float v = o[d0][r] * rl * bf2f(P_gate[idx]);
;       P_og[idx] = f2bf(v);
;     }
;   }
;   __syncthreads();
	v_lshlrev_b32_e32 v35, 16, v35
	v_mul_f32_e32 v0, v36, v0
	v_mul_f32_e32 v5, v37, v5
	v_mul_f32_e32 v34, v38, v34
	v_mul_f32_e32 v28, v28, v35
	v_cvt_pk_bf16_f32 v0, v0, v0
	v_cvt_pk_bf16_f32 v5, v5, v5
	v_cvt_pk_bf16_f32 v34, v34, v34
	v_cvt_pk_bf16_f32 v28, v28, v28
	global_store_short v[12:13], v0, off
	global_store_short v[14:15], v5, off
	global_store_short v[16:17], v34, off
	global_store_short v[6:7], v28, off
	global_load_ushort v0, v[10:11], off
	s_nop 0
	global_load_ushort v5, v[24:25], off
	global_load_ushort v34, v[26:27], off
	s_nop 0
	global_load_ushort v32, v[32:33], off
	v_rcp_f32_e32 v10, v93
	v_or_b32_e32 v6, 26, v4
	v_ashrrev_i32_e32 v7, 31, v6
	v_lshlrev_b64 v[6:7], 12, v[6:7]
	v_mul_f32_e32 v33, v77, v10
	v_lshl_add_u64 v[6:7], v[6:7], 0, v[2:3]
	v_mul_f32_e32 v35, v61, v10
	v_mul_f32_e32 v36, v45, v10
	v_mul_f32_e32 v37, v29, v10
	v_lshlrev_b64 v[6:7], 1, v[6:7]
	v_or_b32_e32 v16, 0x80, v6
	v_mov_b32_e32 v17, v7
	v_lshl_add_u64 v[10:11], s[14:15], 0, v[6:7]
	v_lshl_add_u64 v[12:13], s[12:13], 0, v[6:7]
	v_or_b32_e32 v14, 64, v6
	v_mov_b32_e32 v15, v7
	v_or_b32_e32 v6, 0xc0, v6
	v_lshl_add_u64 v[26:27], s[14:15], 0, v[16:17]
	v_lshl_add_u64 v[24:25], s[14:15], 0, v[14:15]
	v_lshl_add_u64 v[28:29], s[14:15], 0, v[6:7]
	v_or_b32_e32 v4, 27, v4
	v_lshl_add_u64 v[14:15], s[12:13], 0, v[14:15]
	v_lshl_add_u64 v[16:17], s[12:13], 0, v[16:17]
	v_lshl_add_u64 v[6:7], s[12:13], 0, v[6:7]
	s_waitcnt vmcnt(3)
	v_lshlrev_b32_e32 v0, 16, v0
	s_waitcnt vmcnt(2)
	v_lshlrev_b32_e32 v5, 16, v5
	s_waitcnt vmcnt(1)
	v_lshlrev_b32_e32 v34, 16, v34
	s_waitcnt vmcnt(0)
	v_lshlrev_b32_e32 v32, 16, v32
	v_mul_f32_e32 v0, v33, v0
	v_mul_f32_e32 v5, v35, v5
	v_mul_f32_e32 v33, v36, v34
	v_mul_f32_e32 v32, v37, v32
	v_cvt_pk_bf16_f32 v0, v0, v0
	v_cvt_pk_bf16_f32 v5, v5, v5
	v_cvt_pk_bf16_f32 v33, v33, v33
	v_cvt_pk_bf16_f32 v32, v32, v32
	global_store_short v[18:19], v0, off
	global_store_short v[20:21], v5, off
	global_store_short v[22:23], v33, off
	global_store_short v[8:9], v32, off
	global_load_ushort v0, v[10:11], off
	s_nop 0
	global_load_ushort v32, v[24:25], off
	s_nop 0
	global_load_ushort v26, v[26:27], off
	s_nop 0
	global_load_ushort v27, v[28:29], off
	v_rcp_f32_e32 v8, v94
	v_ashrrev_i32_e32 v5, 31, v4
	v_lshlrev_b64 v[4:5], 12, v[4:5]
	v_lshl_add_u64 v[2:3], v[4:5], 0, v[2:3]
	v_mul_f32_e32 v28, v78, v8
	v_mul_f32_e32 v29, v62, v8
	v_mul_f32_e32 v33, v46, v8
	v_mul_f32_e32 v30, v30, v8
	v_lshlrev_b64 v[2:3], 1, v[2:3]
	v_lshl_add_u64 v[4:5], s[14:15], 0, v[2:3]
	v_lshl_add_u64 v[8:9], s[12:13], 0, v[2:3]
	v_or_b32_e32 v10, 64, v2
	v_mov_b32_e32 v11, v3
	v_or_b32_e32 v18, 0x80, v2
	v_mov_b32_e32 v19, v3
	v_or_b32_e32 v2, 0xc0, v2
	v_lshl_add_u64 v[20:21], s[14:15], 0, v[10:11]
	v_lshl_add_u64 v[22:23], s[14:15], 0, v[18:19]
	v_lshl_add_u64 v[24:25], s[14:15], 0, v[2:3]
	v_lshl_add_u64 v[2:3], s[12:13], 0, v[2:3]
	s_waitcnt vmcnt(3)
	v_lshlrev_b32_e32 v0, 16, v0
	s_waitcnt vmcnt(2)
	v_lshlrev_b32_e32 v32, 16, v32
	s_waitcnt vmcnt(1)
	v_lshlrev_b32_e32 v26, 16, v26
	s_waitcnt vmcnt(0)
	v_lshlrev_b32_e32 v27, 16, v27
	v_mul_f32_e32 v0, v28, v0
	v_mul_f32_e32 v28, v29, v32
	v_mul_f32_e32 v26, v33, v26
	v_mul_f32_e32 v27, v30, v27
	v_cvt_pk_bf16_f32 v0, v0, v0
	v_cvt_pk_bf16_f32 v28, v28, v28
	v_cvt_pk_bf16_f32 v26, v26, v26
	v_cvt_pk_bf16_f32 v27, v27, v27
	global_store_short v[12:13], v0, off
	global_store_short v[14:15], v28, off
	global_store_short v[16:17], v26, off
	global_store_short v[6:7], v27, off
	global_load_ushort v0, v[4:5], off
	s_nop 0
	global_load_ushort v12, v[20:21], off
	global_load_ushort v13, v[22:23], off
	global_load_ushort v14, v[24:25], off
	v_rcp_f32_e32 v4, v95
	v_lshl_add_u64 v[6:7], s[12:13], 0, v[18:19]
	v_mul_f32_e32 v15, v79, v4
	v_mul_f32_e32 v16, v63, v4
	v_mul_f32_e32 v17, v47, v4
	v_mul_f32_e32 v20, v31, v4
	v_lshl_add_u64 v[4:5], s[12:13], 0, v[10:11]
	s_waitcnt vmcnt(3)
	v_lshlrev_b32_e32 v0, 16, v0
	s_waitcnt vmcnt(2)
	v_lshlrev_b32_e32 v10, 16, v12
	s_waitcnt vmcnt(1)
	v_lshlrev_b32_e32 v11, 16, v13
	s_waitcnt vmcnt(0)
	v_lshlrev_b32_e32 v12, 16, v14
	v_mul_f32_e32 v0, v15, v0
	v_mul_f32_e32 v10, v16, v10
	v_mul_f32_e32 v11, v17, v11
	v_mul_f32_e32 v12, v20, v12
	v_cvt_pk_bf16_f32 v0, v0, v0
	v_cvt_pk_bf16_f32 v10, v10, v10
	v_cvt_pk_bf16_f32 v11, v11, v11
	v_cvt_pk_bf16_f32 v12, v12, v12
	global_store_short v[8:9], v0, off
	global_store_short v[4:5], v10, off
	global_store_short v[6:7], v11, off
	global_store_short v[2:3], v12, off
	s_barrier
	s_cbranch_scc1 .LBB0_676

; template <int MODE>
; __device__ __forceinline__ void attn_item(const Params& P, int b, int h, int qb, char* lds) {
;     ...
;   for (int it = 0; it < NT; ++it) {
;     const int t = NT - 1 - it, buf = it & 1;
;     asm volatile("s_waitcnt vmcnt(0)" ::: "memory");
;     const u64 mcur = mw;
;     if (MODE == 1) { if (tid < 16) *(f32x4*)(cs_l + buf * 64 + tid * 4) = stc; }
;     __syncthreads();
;     if (it + 1 < NT) LOADT(t - 1, buf ^ 1);
;     const int kb = t * 64;
;     if (kb <= q0 + 31) {
;       f32x16 p0, p1;
;       if (MODE == 1) {
;         const float* cb = cs_l + buf * 64 + 4 * hi;
;         const float cref = c2t - m_reg;
; #pragma unroll
;         for (int q = 0; q < 4; ++q) {
;           const f32x4 ca = *(const f32x4*)(cb + 8 * q), cc = *(const f32x4*)(cb + 32 + 8 * q);
; #pragma unroll
;           for (int e = 0; e < 4; ++e) { p0[q * 4 + e] = cref - ca[e]; p1[q * 4 + e] = cref - cc[e]; }
;         }
;       } else {
;         const float nref = -m_reg;
; #pragma unroll
;         for (int r = 0; r < 16; ++r) { p0[r] = nref; p1[r] = nref; }
;       }
;       {
;         const char* kbp = K_lds + buf * 16384;
; #pragma unroll
;         for (int d0 = 0; d0 < 8; ++d0) {
;           const char* a = kbp + KSWZ(r32, (d0 * 16 + hi * 8) * 2);
;           const bf16x8 b0 = *(const bf16x8*)a;
;           const bf16x8 b1 = *(const bf16x8*)(a + 32 * 256);
;           p0 = __builtin_amdgcn_mfma_f32_32x32x16_bf16(b0, qr[d0], p0, 0, 0, 0);
;           p1 = __builtin_amdgcn_mfma_f32_32x32x16_bf16(b1, qr[d0], p1, 0, 0, 0);
;         }
;       }
;       const float NEG = -__builtin_inff();
;       if (MODE == 0) {
;       } else {
;         if (kb + 63 > q0) {
;           const int dq = qpos - kb - 4 * hi;
; #pragma unroll
;           for (int r = 0; r < 16; ++r) {
;             const int c = (r & 3) + 8 * (r >> 2);
;             if (dq - c < 0) p0[r] = NEG;
;             if (dq - c - 32 < 0) p1[r] = NEG;
;           }
;         }
;       }
;       float pmax = p0[0];
; #pragma unroll
;       for (int r = 1; r < 16; ++r) pmax = fmaxf(pmax, p0[r]);
; #pragma unroll
;       for (int r = 0; r < 16; ++r) pmax = fmaxf(pmax, p1[r]);
;       pmax = fmaxf(pmax, __shfl_xor(pmax, 32));
;       if (!(started && __all(pmax < -160.f))) {
;       float alpha = 1.f;
;       if (!started || __any(pmax > 6.f)) {
;         float delta = started ? fmaxf(pmax, 0.f) : pmax;
.LBB0_682:
	s_and_b32 s9, s59, 0x4000
	s_xor_b32 s1, s9, 0x4000
	v_add_u32_e32 v0, s1, v180
	v_add_u32_e32 v10, 0x8000, v0
	v_lshl_add_u64 v[2:3], s[94:95], 0, v[162:163]
	v_readfirstlane_b32 s1, v10
	v_lshl_add_u64 v[4:5], v[2:3], 0, s[22:23]
	s_mov_b32 m0, s1
	s_waitcnt vmcnt(0)
	s_waitcnt lgkmcnt(0)
	s_barrier
	v_lshl_add_u64 v[6:7], s[94:95], 0, v[164:165]
	global_load_lds_dwordx4 v[4:5], off
	v_readfirstlane_b32 s1, v0
	v_add_u32_e32 v4, 0xa000, v0
	v_lshl_add_u64 v[8:9], v[6:7], 0, s[24:25]
	s_mov_b32 m0, s1
	v_readfirstlane_b32 s1, v4
	v_add_u32_e32 v0, 0x2000, v0
	global_load_lds_dwordx4 v[8:9], off
	v_lshl_add_u64 v[2:3], v[2:3], 0, s[26:27]
	s_mov_b32 m0, s1
	v_readfirstlane_b32 s1, v0
	global_load_lds_dwordx4 v[2:3], off
	v_lshl_add_u64 v[2:3], v[6:7], 0, s[28:29]
	s_mov_b32 m0, s1
	s_cmp_gt_i32 s16, s60
	global_load_lds_dwordx4 v[2:3], off
	v_lshl_add_u64 v[2:3], s[94:95], 0, v[160:161]
	global_load_dwordx2 v[14:15], v[2:3], off
	s_cbranch_scc1 .LBB0_699
	s_cmp_lt_u32 s98, 4
	s_cbranch_scc1 .Lmy_pr_a
	s_setprio 1
.Lmy_pr_a:
	v_add_u32_e32 v0, s9, v182
	v_add_u32_e32 v6, v0, v183
	v_add_u32_e32 v10, v0, v181
	ds_read_b128 v[212:215], v6 offset:32768
	ds_read_b128 v[6:9], v6 offset:40960
	v_add_u32_e32 v187, v0, v179
	ds_read_b128 v[216:219], v10 offset:32768
	ds_read_b128 v[10:13], v10 offset:40960
	v_add_u32_e32 v2, v0, v178
	ds_read_b128 v[220:223], v187 offset:32768
	ds_read_b128 v[188:191], v187 offset:40960
	v_add_u32_e32 v196, v0, v177
	ds_read_b128 v[224:227], v2 offset:32768
	ds_read_b128 v[192:195], v2 offset:40960
	v_add_u32_e32 v3, v0, v176
	ds_read_b128 v[228:231], v196 offset:32768
	ds_read_b128 v[196:199], v196 offset:40960
	v_add_u32_e32 v204, v0, v175
	ds_read_b128 v[232:235], v3 offset:32768
	ds_read_b128 v[200:203], v3 offset:40960
	ds_read_b128 v[236:239], v204 offset:32768
	ds_read_b128 v[204:207], v204 offset:40960
	v_add_u32_e32 v0, v0, v174
	v_xor_b32_e32 v96, 0x80000000, v186
	v_mov_b32_e32 v97, v96
	v_mov_b32_e32 v98, v96
	v_mov_b32_e32 v99, v96
	v_mov_b32_e32 v100, v96
	v_mov_b32_e32 v101, v96
	v_mov_b32_e32 v102, v96
	v_mov_b32_e32 v103, v96
	v_mov_b32_e32 v104, v96
	v_mov_b32_e32 v105, v96
	v_mov_b32_e32 v106, v96
	v_mov_b32_e32 v107, v96
	v_mov_b32_e32 v108, v96
	v_mov_b32_e32 v109, v96
	v_mov_b32_e32 v110, v96
	v_mov_b32_e32 v111, v96
	s_cmp_eq_u32 s0, 0
	s_cselect_b64 s[10:11], -1, 0
	s_cmp_lg_u32 s0, 0
	s_waitcnt lgkmcnt(13)
	v_mfma_f32_32x32x16_bf16 v[112:127], v[212:215], v[156:159], v[96:111]
	ds_read_b128 v[240:243], v0 offset:32768
	ds_read_b128 v[208:211], v0 offset:40960
	s_waitcnt lgkmcnt(14)
	v_mfma_f32_32x32x16_bf16 v[96:111], v[6:9], v[156:159], v[96:111]
	s_waitcnt lgkmcnt(13)
	v_mfma_f32_32x32x16_bf16 v[112:127], v[216:219], v[152:155], v[112:127]
	s_waitcnt lgkmcnt(12)
	v_mfma_f32_32x32x16_bf16 v[96:111], v[10:13], v[152:155], v[96:111]
	s_waitcnt lgkmcnt(11)
	v_mfma_f32_32x32x16_bf16 v[112:127], v[220:223], v[148:151], v[112:127]
	s_waitcnt lgkmcnt(10)
	v_mfma_f32_32x32x16_bf16 v[96:111], v[188:191], v[148:151], v[96:111]
	s_waitcnt lgkmcnt(9)
	v_mfma_f32_32x32x16_bf16 v[112:127], v[224:227], v[144:147], v[112:127]
	s_waitcnt lgkmcnt(8)
	v_mfma_f32_32x32x16_bf16 v[96:111], v[192:195], v[144:147], v[96:111]
	s_waitcnt lgkmcnt(7)
	v_mfma_f32_32x32x16_bf16 v[112:127], v[228:231], v[140:143], v[112:127]
	s_waitcnt lgkmcnt(6)
	v_mfma_f32_32x32x16_bf16 v[96:111], v[196:199], v[140:143], v[96:111]
	s_waitcnt lgkmcnt(5)
	v_mfma_f32_32x32x16_bf16 v[112:127], v[232:235], v[136:139], v[112:127]
	s_waitcnt lgkmcnt(4)
	v_mfma_f32_32x32x16_bf16 v[96:111], v[200:203], v[136:139], v[96:111]
	s_waitcnt lgkmcnt(3)
	v_mfma_f32_32x32x16_bf16 v[112:127], v[236:239], v[132:135], v[112:127]
	s_waitcnt lgkmcnt(2)
	v_mfma_f32_32x32x16_bf16 v[96:111], v[204:207], v[132:135], v[96:111]
	s_waitcnt lgkmcnt(1)
	v_mfma_f32_32x32x16_bf16 v[112:127], v[240:243], v[128:131], v[112:127]
	s_waitcnt lgkmcnt(0)
	v_mfma_f32_32x32x16_bf16 v[96:111], v[208:211], v[128:131], v[96:111]
	s_nop 10
	v_max_f32_e32 v0, v113, v113
	v_max_f32_e32 v2, v112, v112
	v_max_f32_e32 v0, v2, v0
	v_max3_f32 v0, v0, v114, v115
	v_max3_f32 v0, v0, v116, v117
	v_max3_f32 v0, v0, v118, v119
	v_max3_f32 v0, v0, v120, v121
	v_max3_f32 v0, v0, v122, v123
	v_max3_f32 v0, v0, v124, v125
	v_max3_f32 v0, v0, v126, v127
	v_max3_f32 v0, v0, v96, v97
	v_max3_f32 v0, v0, v98, v99
	v_max3_f32 v0, v0, v100, v101
	v_max3_f32 v0, v0, v102, v103
	v_max3_f32 v0, v0, v104, v105
	v_max3_f32 v0, v0, v106, v107
	v_max3_f32 v0, v0, v108, v109
	v_max3_f32 v0, v0, v110, v111
	v_mov_b32_e32 v2, v0
	s_nop 1
	v_permlane32_swap_b32_e32 v0, v2
	v_max_f32_e32 v0, v0, v2
	s_cbranch_scc0 .LBB0_689
	v_cmp_gt_f32_e32 vcc, s45, v0
	s_mov_b64 s[36:37], 0
	s_cmp_lg_u64 vcc, exec
	s_mov_b64 s[34:35], 0
	s_mov_b64 s[38:39], 0
	s_cbranch_scc0 .LBB0_690
	v_cmp_lt_f32_e32 vcc, s46, v0
	s_cbranch_vccz .LBB0_701
	v_max_f32_e32 v2, v0, v0
	v_max_f32_e32 v2, 0, v2
	s_mov_b64 s[38:39], -1
	s_and_b64 vcc, exec, s[36:37]
	s_cbranch_vccnz .LBB0_691

; __device__ __forceinline__ unsigned xb_ld(unsigned* p)              { return __hip_atomic_load(p, __ATOMIC_RELAXED, __HIP_MEMORY_SCOPE_AGENT); }
; __device__ __forceinline__ unsigned xb_add(unsigned* p, unsigned v) { return __hip_atomic_fetch_add(p, v, __ATOMIC_RELAXED, __HIP_MEMORY_SCOPE_AGENT); }
; #define XB_SPIN(cond, bar) do { unsigned _sp = 0; while (cond) { __builtin_amdgcn_s_sleep(1); \
;     if ((++_sp & 255u) == 0u) { if (xb_ld(&(bar)[XB_TMO])) break; if (_sp > XB_SPIN_CAP) { atomicAdd(&(bar)[XB_TMO], 1u); break; } } } } while (0)
; __device__ __forceinline__ void xcd_barrier(const XcdBarrier& b) {
;     asm volatile("s_waitcnt vmcnt(0)" ::: "memory");
;     __syncthreads();
;     if (threadIdx.x == 0) {
;         unsigned* bar = b.bar;
;         __builtin_amdgcn_s_waitcnt(0);
;         const unsigned old = xb_add(&bar[XB_XSUB(b.x)], 1u);
;         const unsigned gen = old / b.nloc;
;         if (old + 1u == (gen + 1u) * b.nloc) {
;             __builtin_amdgcn_fence(__ATOMIC_RELEASE, "agent");
;             asm volatile("s_waitcnt vmcnt(0)" ::: "memory");
;             const unsigned og = xb_add(&bar[XB_TOP], 1u);
;             const unsigned tg = og / b.nx;
;             if (og + 1u == (tg + 1u) * b.nx) xb_add(&bar[XB_TOPGEN], 1u);
;             else XB_SPIN(xb_ld(&bar[XB_TOPGEN]) == tg, bar);
;             __builtin_amdgcn_fence(__ATOMIC_ACQUIRE, "agent");
;             xb_add(&bar[XB_XGEN(b.x)], 1u);
;         } else {
;             XB_SPIN(xb_ld(&bar[XB_XGEN(b.x)]) == gen, bar);
;             __builtin_amdgcn_fence(__ATOMIC_ACQUIRE, "agent");
;         }
.LBB0_967:
	s_barrier
	s_waitcnt vmcnt(0)
	s_barrier
	s_cmp_lt_u32 s98, 4
	s_cbranch_scc1 .Lmy_pr_9
	s_setprio 1
.Lmy_pr_9:
	s_mov_b64 s[0:1], exec
	v_readlane_b32 s2, v250, 0
	v_readlane_b32 s3, v250, 1
	s_and_b64 s[2:3], s[0:1], s[2:3]
	s_mov_b64 exec, s[2:3]
	s_cbranch_execz .LBB0_1004
	s_mov_b64 s[2:3], exec
	v_mbcnt_lo_u32_b32 v0, s2, 0
	v_readlane_b32 s6, v250, 18
	v_mbcnt_hi_u32_b32 v0, s3, v0
	s_lshl_b32 s33, s6, 6
	s_mov_b32 s9, 0
	v_cmp_eq_u32_e32 vcc, 0, v0
	s_waitcnt vmcnt(0) expcnt(0) lgkmcnt(0)
	s_and_saveexec_b64 s[6:7], vcc
	s_cbranch_execz .LBB0_970
	s_add_i32 s8, s33, 0x500
	s_lshl_b64 s[8:9], s[8:9], 2
	s_add_u32 s8, s94, s8
	s_addc_u32 s9, s95, s9
	s_bcnt1_i32_b64 s2, s[2:3]
	v_mov_b32_e32 v1, 0
	v_mov_b32_e32 v2, s2
	global_atomic_add v1, v1, v2, s[8:9] sc0

; __device__ __forceinline__ unsigned xb_ld(unsigned* p)              { return __hip_atomic_load(p, __ATOMIC_RELAXED, __HIP_MEMORY_SCOPE_AGENT); }
; __device__ __forceinline__ unsigned xb_add(unsigned* p, unsigned v) { return __hip_atomic_fetch_add(p, v, __ATOMIC_RELAXED, __HIP_MEMORY_SCOPE_AGENT); }
; #define XB_SPIN(cond, bar) do { unsigned _sp = 0; while (cond) { __builtin_amdgcn_s_sleep(1); \
;     if ((++_sp & 255u) == 0u) { if (xb_ld(&(bar)[XB_TMO])) break; if (_sp > XB_SPIN_CAP) { atomicAdd(&(bar)[XB_TMO], 1u); break; } } } } while (0)
; __device__ __forceinline__ void xcd_barrier(const XcdBarrier& b) {
;     asm volatile("s_waitcnt vmcnt(0)" ::: "memory");
;     __syncthreads();
;     if (threadIdx.x == 0) {
;         unsigned* bar = b.bar;
;         __builtin_amdgcn_s_waitcnt(0);
;         const unsigned old = xb_add(&bar[XB_XSUB(b.x)], 1u);
;         const unsigned gen = old / b.nloc;
;         if (old + 1u == (gen + 1u) * b.nloc) {
;             __builtin_amdgcn_fence(__ATOMIC_RELEASE, "agent");
;             asm volatile("s_waitcnt vmcnt(0)" ::: "memory");
;             const unsigned og = xb_add(&bar[XB_TOP], 1u);
;             const unsigned tg = og / b.nx;
;             if (og + 1u == (tg + 1u) * b.nx) xb_add(&bar[XB_TOPGEN], 1u);
;             else XB_SPIN(xb_ld(&bar[XB_TOPGEN]) == tg, bar);
;             __builtin_amdgcn_fence(__ATOMIC_ACQUIRE, "agent");
;             xb_add(&bar[XB_XGEN(b.x)], 1u);
;         } else {
;             XB_SPIN(xb_ld(&bar[XB_XGEN(b.x)]) == gen, bar);
;             __builtin_amdgcn_fence(__ATOMIC_ACQUIRE, "agent");
;         }
.LBB0_1042:
	s_waitcnt vmcnt(0)
	s_barrier
	s_setprio 0
	s_mov_b64 s[0:1], exec
	v_readlane_b32 s2, v250, 0
	v_readlane_b32 s3, v250, 1
	s_and_b64 s[2:3], s[0:1], s[2:3]
	s_xor_b64 s[0:1], s[2:3], s[0:1]
	s_mov_b64 exec, s[2:3]
	s_cbranch_execz .LBB0_1080
	s_mov_b64 s[2:3], exec
	v_mbcnt_lo_u32_b32 v0, s2, 0
	v_readlane_b32 s4, v250, 18
	v_mbcnt_hi_u32_b32 v0, s3, v0
	s_lshl_b32 s30, s4, 6
	s_mov_b32 s7, 0
	v_cmp_eq_u32_e32 vcc, 0, v0
	s_waitcnt vmcnt(0) expcnt(0) lgkmcnt(0)
	s_and_saveexec_b64 s[4:5], vcc
	s_cbranch_execz .LBB0_1045
	s_add_i32 s6, s30, 0x500
	s_lshl_b64 s[6:7], s[6:7], 2
	s_add_u32 s6, s94, s6
	s_addc_u32 s7, s95, s7
	s_bcnt1_i32_b64 s2, s[2:3]
	v_mov_b32_e32 v1, 0
	v_mov_b32_e32 v2, s2
	global_atomic_add v1, v1, v2, s[6:7] sc0
